# grid barrier: non-leader workgroups poll the global generation word directly instead of the per-XCD relay word
# baseline (speedup 1.0000x reference)
; __device__ __forceinline__ unsigned xb_ld(unsigned* p)              { return __hip_atomic_load(p, __ATOMIC_RELAXED, __HIP_MEMORY_SCOPE_AGENT); }
; __device__ __forceinline__ unsigned xb_add(unsigned* p, unsigned v) { return __hip_atomic_fetch_add(p, v, __ATOMIC_RELAXED, __HIP_MEMORY_SCOPE_AGENT); }
; #define XB_SPIN(cond, bar) do { unsigned _sp = 0; while (cond) { __builtin_amdgcn_s_sleep(1); \
;     if ((++_sp & 255u) == 0u) { if (xb_ld(&(bar)[XB_TMO])) break; if (_sp > XB_SPIN_CAP) { atomicAdd(&(bar)[XB_TMO], 1u); break; } } } } while (0)
; __device__ __forceinline__ void xcd_barrier(const XcdBarrier& b) {
;     ...
;         const unsigned old = xb_add(&bar[XB_XSUB(b.x)], 1u);
;         const unsigned gen = old / nloc;
;         if (old + 1u == (gen + 1u) * nloc) {
;             __builtin_amdgcn_fence(__ATOMIC_RELEASE, "agent");
;             asm volatile("s_waitcnt vmcnt(0)" ::: "memory");
;             const unsigned og = xb_add(&bar[XB_TOP], 1u);
;             const unsigned tg = og / nx;
;             if (og + 1u == (tg + 1u) * nx) xb_add(&bar[XB_TOPGEN], 1u);
;             else XB_SPIN(xb_ld(&bar[XB_TOPGEN]) == tg, bar);
;             __builtin_amdgcn_fence(__ATOMIC_ACQUIRE, "agent");
;             xb_add(&bar[XB_XGEN(b.x)], 1u);
;             asm volatile("s_waitcnt vmcnt(0)" ::: "memory");
;         } else {
;             XB_SPIN(xb_ld(&bar[XB_XGEN(b.x)]) == gen, bar);
;             __builtin_amdgcn_fence(__ATOMIC_ACQUIRE, "agent");
;             asm volatile("s_waitcnt vmcnt(0)" ::: "memory");
;         }
.LBB0_971:
	s_or_b64 exec, exec, s[2:3]
	v_cvt_f32_u32_e32 v5, v3
	s_waitcnt vmcnt(0)
	v_readfirstlane_b32 s2, v4
	v_sub_u32_e32 v4, 0, v3
	v_rcp_iflag_f32_e32 v5, v5
	v_add_u32_e32 v6, s2, v0
	v_mul_f32_e32 v5, 0x4f7ffffe, v5
	v_cvt_u32_f32_e32 v5, v5
	v_mul_lo_u32 v0, v4, v5
	v_mul_hi_u32 v0, v5, v0
	v_add_u32_e32 v0, v5, v0
	v_mul_hi_u32 v0, v6, v0
	v_mul_lo_u32 v4, v0, v3
	v_sub_u32_e32 v4, v6, v4
	v_add_u32_e32 v5, 1, v0
	v_cmp_ge_u32_e32 vcc, v4, v3
	s_nop 1
	v_cndmask_b32_e32 v0, v0, v5, vcc
	v_sub_u32_e32 v5, v4, v3
	v_cndmask_b32_e32 v4, v4, v5, vcc
	v_add_u32_e32 v5, 1, v0
	v_cmp_ge_u32_e32 vcc, v4, v3
	v_add_u32_e32 v4, 1, v6
	s_nop 0
	v_cndmask_b32_e32 v0, v0, v5, vcc
	v_mul_lo_u32 v5, v3, v0
	v_add_u32_e32 v3, v5, v3
	v_cmp_ne_u32_e32 vcc, v4, v3
	s_and_saveexec_b64 s[2:3], vcc
	s_xor_b64 s[2:3], exec, s[2:3]
	s_cbranch_execz .LBB0_985
	v_readlane_b32 s6, v254, 52
	v_readlane_b32 s7, v254, 53
	s_waitcnt lgkmcnt(0)
	s_nop 3
	global_load_dword v2, v1, s[6:7] sc1
	s_waitcnt vmcnt(0)
	v_cmp_eq_u32_e32 vcc, v2, v0
	s_and_saveexec_b64 s[6:7], vcc
	s_cbranch_execz .LBB0_984
	s_mov_b32 s5, 1
	s_mov_b64 s[26:27], 0
	s_branch .LBB0_975
